# v113 + K-loop LDS-DMA loads with SGPR base + 32-bit offset (no 64-bit VALU add) + G5 epilogue second scale-broadcast group issued before the first wait
# speedup vs baseline: 1.0326x; 1.0030x over previous
.LBB0_1261:
	v_mbcnt_lo_u32_b32 v137, -1, 0
	v_mbcnt_hi_u32_b32 v137, -1, v137
	s_waitcnt vmcnt(0)
	v_mov_b32_e32 v139, v10
	v_ashrrev_i32_e32 v138, 4, v137
	v_and_b32_e32 v183, 15, v137
	v_lshl_add_u32 v144, v138, 3, s66
	v_lshlrev_b32_e32 v137, 6, v138
	v_lshlrev_b32_e32 v138, 2, v183
	v_add3_u32 v137, s74, v137, v138
	v_mov_b32_e32 v138, v9
	v_mov_b32_e32 v9, v11
	v_pk_add_f32 v[8:9], v[138:139], v[8:9]
	ds_write_b32 v137, v136 offset:4096
	v_add_f32_e32 v8, v8, v9
	v_fmamk_f32 v8, v8, 0x3a800000, v206
	v_rsq_f32_e32 v8, v8
	v_or_b32_e32 v9, v183, v191
	v_lshlrev_b32_e32 v10, 2, v9
	v_mov_b32_e32 v9, v6
	ds_bpermute_b32 v156, v10, v8
	ds_bpermute_b32 v196, v10, v8 offset:64
	ds_bpermute_b32 v192, v10, v8 offset:128
	ds_bpermute_b32 v188, v10, v8 offset:192
	v_mov_b32_e32 v8, v5
	v_mov_b32_e32 v5, v7
	v_pk_add_f32 v[4:5], v[8:9], v[4:5]
	v_lshl_add_u32 v184, s4, 7, v144
	v_add_f32_e32 v4, v4, v5
	v_fmamk_f32 v4, v4, 0x3a800000, v206
	v_rsq_f32_e32 v4, v4
	s_nop 0
	ds_bpermute_b32 v182, v10, v4 offset:192
	ds_bpermute_b32 v194, v10, v4
	ds_bpermute_b32 v190, v10, v4 offset:64
	ds_bpermute_b32 v186, v10, v4 offset:128
	s_waitcnt lgkmcnt(4)
	v_pk_mul_f32 v[138:139], v[42:43], v[188:189] op_sel_hi:[1,0]
	v_pk_mul_f32 v[136:137], v[40:41], v[188:189] op_sel_hi:[1,0]
	v_pk_mul_f32 v[142:143], v[38:39], v[188:189] op_sel_hi:[1,0]
	v_pk_mul_f32 v[140:141], v[36:37], v[188:189] op_sel_hi:[1,0]
	s_waitcnt lgkmcnt(3)
	v_pk_mul_f32 v[8:9], v[20:21], v[182:183] op_sel_hi:[1,0]
	v_cndmask_b32_e64 v20, 0, 1, s[12:13]
	v_pk_mul_f32 v[6:7], v[26:27], v[182:183] op_sel_hi:[1,0]
	v_pk_mul_f32 v[4:5], v[24:25], v[182:183] op_sel_hi:[1,0]
	v_pk_mul_f32 v[10:11], v[22:23], v[182:183] op_sel_hi:[1,0]
	v_cmp_lt_u32_e32 vcc, 13, v183
	v_lshlrev_b32_e32 v209, 2, v144
	v_cmp_ne_u32_e64 s[4:5], 1, v20
	s_and_saveexec_b64 s[56:57], vcc
	s_cbranch_execz .LBB0_1264
	v_add_lshl_u32 v20, s71, v183, 9
	v_add3_u32 v21, s72, v20, v209
	v_add3_u32 v20, s80, v20, v209
	s_and_b64 vcc, exec, s[4:5]
	ds_write_b128 v21, v[136:139]
	ds_write_b128 v21, v[140:143] offset:16
	ds_write_b128 v20, v[4:7]
	ds_write_b128 v21, v[8:11] offset:2064
	s_cbranch_vccnz .LBB0_1264
	s_ashr_i32 s55, s54, 31
	v_add_u32_e32 v176, -14, v183
	v_lshl_add_u64 v[20:21], s[54:55], 1, v[176:177]
	v_mov_b64_e32 v[22:23], s[22:23]
	v_mad_u64_u32 v[22:23], s[58:59], v20, s81, v[22:23]
	v_mad_i32_i24 v23, v21, s81, v23
	v_ashrrev_i32_e32 v185, 31, v184
	v_lshl_add_u64 v[20:21], v[184:185], 2, v[22:23]
	global_store_dwordx4 v[20:21], v[4:7], off
	global_store_dwordx4 v[20:21], v[8:11], off offset:16
